# ssd_out inter-chunk term: 16 state-fragment loads pipelined two k-steps deep (hand-written block)
# baseline (speedup 1.0000x reference)
.LBB0_906:
	s_or_b64 exec, exec, s[4:5]
	v_cvt_pk_bf16_f32 v82, v111, v80
	v_cvt_pk_bf16_f32 v83, v72, v74
	v_cvt_pk_bf16_f32 v84, v73, v81
	v_cvt_pk_bf16_f32 v85, v75, v5
	s_cmp_eq_u32 s58, 0
	v_mov_b32_e32 v5, 0
	v_mfma_f32_16x16x32_bf16 v[20:23], v[36:39], v[82:85], v[20:23]
	v_mov_b32_e32 v6, 0
	v_mov_b32_e32 v7, 0
	v_mov_b32_e32 v36, 0
	v_mfma_f32_16x16x32_bf16 v[12:15], v[12:15], v[82:85], v[28:31]
	v_mov_b32_e32 v37, 0
	v_mov_b32_e32 v38, 0
	v_mov_b32_e32 v39, 0
	v_mfma_f32_16x16x32_bf16 v[8:11], v[32:35], v[82:85], v[8:11]
	v_mov_b32_e32 v28, 0
	v_mov_b32_e32 v29, 0
	v_mov_b32_e32 v30, 0
	v_mfma_f32_16x16x32_bf16 v[0:3], v[52:55], v[82:85], v[0:3]
	v_mov_b32_e32 v31, 0
	v_mov_b32_e32 v32, 0
	v_mov_b32_e32 v33, 0
	v_mov_b32_e32 v34, 0
	v_mov_b32_e32 v35, 0
	v_mov_b32_e32 v52, 0
	v_mov_b32_e32 v53, 0
	v_mov_b32_e32 v54, 0
	v_mov_b32_e32 v55, 0
	v_mov_b32_e32 v72, 0
	v_mov_b32_e32 v73, 0
	v_mov_b32_e32 v74, 0
	v_mov_b32_e32 v75, 0
	v_mov_b32_e32 v80, 0
	v_mov_b32_e32 v81, 0
	v_mov_b32_e32 v82, 0
	v_mov_b32_e32 v83, 0
	v_mov_b32_e32 v84, 0
	v_mov_b32_e32 v85, 0
	v_mov_b32_e32 v86, 0
	v_mov_b32_e32 v87, 0
	v_mov_b32_e32 v96, 0
	v_mov_b32_e32 v97, 0
	v_mov_b32_e32 v98, 0
	v_mov_b32_e32 v99, 0
	v_mov_b32_e32 v100, 0
	v_mov_b32_e32 v101, 0
	v_mov_b32_e32 v102, 0
	v_mov_b32_e32 v103, 0
	v_mov_b32_e32 v104, 0
	v_mov_b32_e32 v105, 0
	v_mov_b32_e32 v106, 0
	v_mov_b32_e32 v107, 0
	v_mov_b32_e32 v108, 0
	v_mov_b32_e32 v109, 0
	v_mov_b32_e32 v110, 0
	v_mov_b32_e32 v111, 0
	v_mov_b32_e32 v112, 0
	v_mov_b32_e32 v113, 0
	v_mov_b32_e32 v114, 0
	v_mov_b32_e32 v115, 0
	v_mov_b32_e32 v116, 0
	v_mov_b32_e32 v117, 0
	v_mov_b32_e32 v118, 0
	v_mov_b32_e32 v119, 0
	v_mov_b32_e32 v120, 0
	v_mov_b32_e32 v121, 0
	v_mov_b32_e32 v122, 0
	v_mov_b32_e32 v123, 0
	v_mov_b32_e32 v124, 0
	v_mov_b32_e32 v125, 0
	v_mov_b32_e32 v126, 0
	v_mov_b32_e32 v127, 0
	s_cbranch_scc1 .LBB0_908
	s_lshl_b32 s4, s30, 9
	v_lshlrev_b32_e32 v4, 5, v128
	s_or_b32 s4, s58, s4
	v_add3_u32 v4, s4, -1, v4
	v_ashrrev_i32_e32 v5, 31, v4
	v_readlane_b32 s4, v240, 54
	v_lshlrev_b64 v[4:5], 14, v[4:5]
	v_readlane_b32 s5, v240, 55
	v_lshlrev_b32_e32 v168, 1, v129
	v_and_b32_e32 v6, 48, v142
	v_lshl_add_u64 v[4:5], s[4:5], 0, v[4:5]
	v_lshl_add_u64 v[118:119], v[4:5], 0, v[168:169]
	v_readlane_b32 s4, v239, 35
	v_lshlrev_b32_e32 v168, 8, v144
	v_lshl_add_u64 v[116:117], v[118:119], 0, v[168:169]
	v_add3_u32 v137, s4, v6, v130
	v_mov_b32_e32 v244, v116
	v_mov_b32_e32 v245, v117
	v_add_co_u32_e32 v246, vcc, 0x1000, v116
	v_addc_co_u32_e32 v247, vcc, 0, v117, vcc
	v_add_co_u32_e32 v248, vcc, 0x2000, v116
	v_addc_co_u32_e32 v249, vcc, 0, v117, vcc
	v_add_co_u32_e32 v250, vcc, 0x3000, v116
	v_addc_co_u32_e32 v251, vcc, 0, v117, vcc
	v_mov_b32_e32 v252, v137
	global_load_dwordx4 v[132:135], v[244:245], off
	global_load_dwordx4 v[156:159], v[246:247], off
	global_load_dwordx4 v[160:163], v[248:249], off
	global_load_dwordx4 v[164:167], v[250:251], off
	global_load_dwordx4 v[196:199], v[244:245], off offset:64
	global_load_dwordx4 v[200:203], v[246:247], off offset:64
	global_load_dwordx4 v[204:207], v[248:249], off offset:64
	global_load_dwordx4 v[208:211], v[250:251], off offset:64
	ds_read_b128 v[212:215], v252
	ds_read_b128 v[216:219], v252 offset:4352
	ds_read_b128 v[220:223], v252 offset:8704
	ds_read_b128 v[224:227], v252 offset:13056
	s_waitcnt vmcnt(4) lgkmcnt(0)
	v_mfma_f32_16x16x32_bf16 v[124:127], v[132:135], v[212:215], 0
	v_mfma_f32_16x16x32_bf16 v[108:111], v[132:135], v[216:219], 0
	v_mfma_f32_16x16x32_bf16 v[84:87], v[132:135], v[220:223], 0
	v_mfma_f32_16x16x32_bf16 v[36:39], v[132:135], v[224:227], 0
	v_mfma_f32_16x16x32_bf16 v[120:123], v[156:159], v[212:215], 0
	v_mfma_f32_16x16x32_bf16 v[104:107], v[156:159], v[216:219], 0
	v_mfma_f32_16x16x32_bf16 v[80:83], v[156:159], v[220:223], 0
	v_mfma_f32_16x16x32_bf16 v[32:35], v[156:159], v[224:227], 0
	v_mfma_f32_16x16x32_bf16 v[116:119], v[160:163], v[212:215], 0
	v_mfma_f32_16x16x32_bf16 v[100:103], v[160:163], v[216:219], 0
	v_mfma_f32_16x16x32_bf16 v[72:75], v[160:163], v[220:223], 0
	v_mfma_f32_16x16x32_bf16 v[28:31], v[160:163], v[224:227], 0
	v_mfma_f32_16x16x32_bf16 v[112:115], v[164:167], v[212:215], 0
	v_mfma_f32_16x16x32_bf16 v[96:99], v[164:167], v[216:219], 0
	v_mfma_f32_16x16x32_bf16 v[52:55], v[164:167], v[220:223], 0
	v_mfma_f32_16x16x32_bf16 v[4:7], v[164:167], v[224:227], 0
	global_load_dwordx4 v[132:135], v[244:245], off offset:128
	global_load_dwordx4 v[156:159], v[246:247], off offset:128
	global_load_dwordx4 v[160:163], v[248:249], off offset:128
	global_load_dwordx4 v[164:167], v[250:251], off offset:128
	ds_read_b128 v[212:215], v252 offset:64
	ds_read_b128 v[216:219], v252 offset:4416
	ds_read_b128 v[220:223], v252 offset:8768
	ds_read_b128 v[224:227], v252 offset:13120
	s_waitcnt vmcnt(4) lgkmcnt(0)
	v_mfma_f32_16x16x32_bf16 v[124:127], v[196:199], v[212:215], v[124:127]
	v_mfma_f32_16x16x32_bf16 v[108:111], v[196:199], v[216:219], v[108:111]
	v_mfma_f32_16x16x32_bf16 v[84:87], v[196:199], v[220:223], v[84:87]
	v_mfma_f32_16x16x32_bf16 v[36:39], v[196:199], v[224:227], v[36:39]
	v_mfma_f32_16x16x32_bf16 v[120:123], v[200:203], v[212:215], v[120:123]
	v_mfma_f32_16x16x32_bf16 v[104:107], v[200:203], v[216:219], v[104:107]
	v_mfma_f32_16x16x32_bf16 v[80:83], v[200:203], v[220:223], v[80:83]
	v_mfma_f32_16x16x32_bf16 v[32:35], v[200:203], v[224:227], v[32:35]
	v_mfma_f32_16x16x32_bf16 v[116:119], v[204:207], v[212:215], v[116:119]
	v_mfma_f32_16x16x32_bf16 v[100:103], v[204:207], v[216:219], v[100:103]
	v_mfma_f32_16x16x32_bf16 v[72:75], v[204:207], v[220:223], v[72:75]
	v_mfma_f32_16x16x32_bf16 v[28:31], v[204:207], v[224:227], v[28:31]
	v_mfma_f32_16x16x32_bf16 v[112:115], v[208:211], v[212:215], v[112:115]
	v_mfma_f32_16x16x32_bf16 v[96:99], v[208:211], v[216:219], v[96:99]
	v_mfma_f32_16x16x32_bf16 v[52:55], v[208:211], v[220:223], v[52:55]
	v_mfma_f32_16x16x32_bf16 v[4:7], v[208:211], v[224:227], v[4:7]
	global_load_dwordx4 v[196:199], v[244:245], off offset:192
	global_load_dwordx4 v[200:203], v[246:247], off offset:192
	global_load_dwordx4 v[204:207], v[248:249], off offset:192
	global_load_dwordx4 v[208:211], v[250:251], off offset:192
	ds_read_b128 v[212:215], v252 offset:128
	ds_read_b128 v[216:219], v252 offset:4480
	ds_read_b128 v[220:223], v252 offset:8832
	ds_read_b128 v[224:227], v252 offset:13184
	s_waitcnt vmcnt(4) lgkmcnt(0)
	v_mfma_f32_16x16x32_bf16 v[124:127], v[132:135], v[212:215], v[124:127]
	v_mfma_f32_16x16x32_bf16 v[108:111], v[132:135], v[216:219], v[108:111]
	v_mfma_f32_16x16x32_bf16 v[84:87], v[132:135], v[220:223], v[84:87]
	v_mfma_f32_16x16x32_bf16 v[36:39], v[132:135], v[224:227], v[36:39]
	v_mfma_f32_16x16x32_bf16 v[120:123], v[156:159], v[212:215], v[120:123]
	v_mfma_f32_16x16x32_bf16 v[104:107], v[156:159], v[216:219], v[104:107]
	v_mfma_f32_16x16x32_bf16 v[80:83], v[156:159], v[220:223], v[80:83]
	v_mfma_f32_16x16x32_bf16 v[32:35], v[156:159], v[224:227], v[32:35]
	v_mfma_f32_16x16x32_bf16 v[116:119], v[160:163], v[212:215], v[116:119]
	v_mfma_f32_16x16x32_bf16 v[100:103], v[160:163], v[216:219], v[100:103]
	v_mfma_f32_16x16x32_bf16 v[72:75], v[160:163], v[220:223], v[72:75]
	v_mfma_f32_16x16x32_bf16 v[28:31], v[160:163], v[224:227], v[28:31]
	v_mfma_f32_16x16x32_bf16 v[112:115], v[164:167], v[212:215], v[112:115]
	v_mfma_f32_16x16x32_bf16 v[96:99], v[164:167], v[216:219], v[96:99]
	v_mfma_f32_16x16x32_bf16 v[52:55], v[164:167], v[220:223], v[52:55]
	v_mfma_f32_16x16x32_bf16 v[4:7], v[164:167], v[224:227], v[4:7]
	ds_read_b128 v[212:215], v252 offset:192
	ds_read_b128 v[216:219], v252 offset:4544
	ds_read_b128 v[220:223], v252 offset:8896
	ds_read_b128 v[224:227], v252 offset:13248
	s_waitcnt vmcnt(0) lgkmcnt(0)
	v_mfma_f32_16x16x32_bf16 v[124:127], v[196:199], v[212:215], v[124:127]
	v_mfma_f32_16x16x32_bf16 v[108:111], v[196:199], v[216:219], v[108:111]
	v_mfma_f32_16x16x32_bf16 v[84:87], v[196:199], v[220:223], v[84:87]
	v_mfma_f32_16x16x32_bf16 v[36:39], v[196:199], v[224:227], v[36:39]
	v_mfma_f32_16x16x32_bf16 v[120:123], v[200:203], v[212:215], v[120:123]
	v_mfma_f32_16x16x32_bf16 v[104:107], v[200:203], v[216:219], v[104:107]
	v_mfma_f32_16x16x32_bf16 v[80:83], v[200:203], v[220:223], v[80:83]
	v_mfma_f32_16x16x32_bf16 v[32:35], v[200:203], v[224:227], v[32:35]
	v_mfma_f32_16x16x32_bf16 v[116:119], v[204:207], v[212:215], v[116:119]
	v_mfma_f32_16x16x32_bf16 v[100:103], v[204:207], v[216:219], v[100:103]
	v_mfma_f32_16x16x32_bf16 v[72:75], v[204:207], v[220:223], v[72:75]
	v_mfma_f32_16x16x32_bf16 v[28:31], v[204:207], v[224:227], v[28:31]
	v_mfma_f32_16x16x32_bf16 v[112:115], v[208:211], v[212:215], v[112:115]
	v_mfma_f32_16x16x32_bf16 v[96:99], v[208:211], v[216:219], v[96:99]
	v_mfma_f32_16x16x32_bf16 v[52:55], v[208:211], v[220:223], v[52:55]
	v_mfma_f32_16x16x32_bf16 v[4:7], v[208:211], v[224:227], v[4:7]
	s_nop 7
	s_nop 7
